# one static s_setprio 1 for waves 4-7 inside the two attention loops (guide 7.4), reset after the phase
# speedup vs baseline: 1.0085x; 1.0008x over previous
; __global__ void __launch_bounds__(512, 2) fwd_mega(Args a) {
;     ...
;         { const int vcu = (blk & 7) * 32 + (blk >> 3), xi = vcu & 31, xc = vcu >> 5; const bool xm = (G == 256);
; #pragma nounroll
;           for (int k = 0; k < (xm ? 4 : (1024 + G - 1) / G); ++k) {
;               int u = blk + k * G;
;               if (xm) u = k < 2 ? 2 * vcu + k : 512 + (4 * xc + 2 * (k - 2) + (xi >> 4)) * 16 + (xi & 15);
;               if (u >= 1024) break;
;               if (u < 512) att::attn_win(lds, u, QKG, Vt, OA, a.in[11] + l * 8);
;               else att::attn_na(lds, u - 512, QKG, Vt, OB, a.in[12] + (size_t)l * 8 * 15 * 31);
;           } }
.LBB0_597:
	v_readfirstlane_b32 s101, v202
	s_bitcmp1_b32 s101, 8
	s_cbranch_scc0 .Lmy_noprio_0
	s_setprio 1

; __device__ __forceinline__ unsigned xb_add(unsigned* p, unsigned v) { return __hip_atomic_fetch_add(p, v, __ATOMIC_RELAXED, __HIP_MEMORY_SCOPE_AGENT); }
; __device__ __forceinline__ void xcd_barrier(const XcdBarrier& b) {
;     asm volatile("s_waitcnt vmcnt(0)" ::: "memory");
;     __syncthreads();
;     if (threadIdx.x == 0) {
;         unsigned* bar = b.bar;
;         __builtin_amdgcn_s_waitcnt(0);
;         unsigned nloc = b.st[0], nx = b.st[1];
;         if (nloc == 0u) { xcd_barrier_complete(bar, b.x, nloc, nx); b.st[0] = nloc; b.st[1] = nx; }
;         const unsigned old = xb_add(&bar[XB_XSUB(b.x)], 1u);
.LBB0_624:
	s_setprio 0
	s_waitcnt vmcnt(0)
	s_barrier
	s_and_saveexec_b64 s[0:1], s[80:81]
	s_cbranch_execz .LBB0_672
	v_readlane_b32 s4, v254, 41
	s_waitcnt vmcnt(0) expcnt(0) lgkmcnt(0)
	s_nop 0
	v_mov_b32_e32 v0, s4
	ds_read_b32 v3, v0
	v_readlane_b32 s4, v254, 42
	s_waitcnt lgkmcnt(0)
	v_cmp_ne_u32_e32 vcc, 0, v3
	v_mov_b32_e32 v0, s4
	ds_read_b32 v2, v0
	s_cbranch_vccnz .LBB0_640
	s_mov_b32 s4, 1
	s_branch .LBB0_628
